# FoX unit prologue: the two masked load+vmcnt(0) round trips (ck, cend) merged into the common wait (one round trip instead of three for wave 0)
# baseline (speedup 1.0000x reference)
; #define FX_LOAD(T) do { const bf16_t* rp = proj + (rowbase + 128 * (T) + krow) * NPROJ + h * 64 + chunk * 8; \
;         kreg[0] = *(const u32x4*)(rp + C_FK); kreg[1] = *(const u32x4*)(rp + C_FK + 32); vreg[0] = *(const u32x4*)(rp + C_FV); vreg[1] = *(const u32x4*)(rp + C_FV + 32); \
;         if (tid < 128) ckreg = FX_C2(128 * (T) + tid); } while (0)
; DI void fox_unit(int bh, int qb, const Params& p, LAS unsigned char* lds, float thr2) {
;     ...
;     const int krow = tid & 127, chunk = tid >> 7;
;     u32x4 kreg[2], vreg[2]; float ckreg = 0.f;
;     ...
;     FX_LOAD(T_hi);
.LBB0_507:
	s_lshl_b32 s8, s0, 11
	s_or_b32 s30, s8, s1
	s_lshr_b32 s8, s30, 7
	s_or_b32 s18, s8, 1
	v_mov_b32_e32 v212, v208
	s_lshl_b32 s9, s18, 7
	s_add_u32 s8, s26, s9
	v_and_b32_e32 v4, 0x7f, v212
	v_or_b32_e32 v0, s8, v4
	v_mad_u64_u32 v[6:7], s[22:23], v0, s5, v[166:167]
	v_ashrrev_i32_e32 v0, 4, v212
	s_addc_u32 s19, s27, 0
	v_and_b32_e32 v2, -8, v0
	v_mad_i32_i24 v7, s19, v206, v7
	v_ashrrev_i32_e32 v3, 31, v2
	v_lshl_add_u64 v[6:7], v[2:3], 1, v[6:7]
	global_load_dwordx4 v[98:101], v[6:7], off offset:1024
	global_load_dwordx4 v[102:105], v[6:7], off offset:1088
	global_load_dwordx4 v[106:109], v[6:7], off offset:2048
	global_load_dwordx4 v[110:113], v[6:7], off offset:2112
	s_movk_i32 s19, 0x80
	v_readfirstlane_b32 s8, v212
	v_cmp_gt_i32_e64 s[38:39], s19, v212
	v_mov_b32_e32 v215, 0
	s_and_saveexec_b64 s[22:23], s[38:39]
	s_cbranch_execz .LBB0_509
	v_add_u32_e32 v6, s9, v212
	v_ashrrev_i32_e32 v7, 31, v6
	v_ashrrev_i32_e32 v0, 6, v6
	v_lshl_add_u64 v[6:7], v[6:7], 2, s[28:29]
	global_load_dword v236, v[6:7], off
	v_lshl_add_u32 v0, v0, 2, 0
	v_add_u32_e32 v0, 0x12400, v0
	ds_read_b32 v237, v0

; DI void fox_unit(int bh, int qb, const Params& p, LAS unsigned char* lds, float thr2) {
;     ...
;     const float cq0 = FX_C2(q0), cq = FX_C2(qrow);
;     const float cend = (tid < q0 / 64) ? FX_C2(64 * tid + 63) : 0.f;
;     __syncthreads();
;     if (tid < q0 / 64) { if (cq0 - cend >= -thr2) atomicMin((int*)tlo, tid); }
.LBB0_513:
	s_or_b64 exec, exec, s[22:23]
	s_waitcnt vmcnt(0) lgkmcnt(0)
	v_add_f32_e32 v215, v237, v236
	v_add_f32_e32 v10, v12, v10
	v_add_f32_e32 v8, v9, v8
	v_sub_f32_e32 v8, v8, v10
	v_cmp_ge_f32_e64 s[22:23], v8, -v207
	s_xor_b64 s[34:35], vcc, -1
	s_and_b64 s[34:35], s[34:35], s[22:23]
	s_waitcnt lgkmcnt(0)
	s_barrier
	s_and_saveexec_b64 s[22:23], s[34:35]
	s_cbranch_execz .LBB0_518
	s_mov_b64 s[40:41], exec
	s_brev_b32 s9, -2
